# v18: FoX loop - rescale accumulators in place, drop the 56 per-step accumulator copies
# speedup vs baseline: 1.0017x; 1.0017x over previous
.LBB0_399:
	s_nop 10
	v_cndmask_b32_e64 v97, 0, 1, s[14:15]
	v_cmp_ne_u32_e64 s[42:43], 1, v97
	s_andn2_b64 vcc, exec, s[14:15]
	s_cbranch_vccnz .LBB0_401
	s_waitcnt vmcnt(0)
	ds_write_b128 v241, v[208:211]

.LBB0_415:
	v_max_f32_e32 v97, v161, v161
	v_max_f32_e32 v98, v160, v160
	v_max_f32_e32 v97, v98, v97
	v_max3_f32 v97, v97, v162, v163
	v_max3_f32 v97, v97, v164, v165
	v_max3_f32 v97, v97, v166, v167
	v_max3_f32 v97, v97, v168, v169
	v_max3_f32 v97, v97, v170, v171
	v_max3_f32 v97, v97, v172, v173
	v_max3_f32 v97, v97, v174, v175
	v_max3_f32 v97, v97, v176, v177
	v_max3_f32 v97, v97, v178, v179
	v_max3_f32 v97, v97, v180, v181
	v_max3_f32 v97, v97, v182, v183
	v_max3_f32 v97, v97, v184, v185
	v_max3_f32 v97, v97, v186, v187
	v_max3_f32 v97, v97, v188, v189
	v_max3_f32 v97, v97, v190, v191
	v_mov_b32_e32 v98, v97
	v_mov_b32_e32 v99, v97
	s_nop 1
	v_permlane32_swap_b32_e32 v98, v99
	v_cndmask_b32_e64 v98, v98, v99, s[38:39]
	v_max3_f32 v97, v96, v97, v98
	v_cmp_neq_f32_e32 vcc, s2, v97
	s_nop 1
	v_cndmask_b32_e32 v98, 0, v97, vcc
	v_sub_f32_e32 v96, v96, v98
	v_exp_f32_e32 v96, v96
	s_nop 0
	v_cmp_eq_f32_e32 vcc, 1.0, v96
	s_cmp_eq_u64 vcc, exec
	s_cbranch_scc1 .LBB0_417
	v_pk_mul_f32 v[46:47], v[46:47], v[96:97] op_sel_hi:[1,0]
	v_pk_mul_f32 v[44:45], v[44:45], v[96:97] op_sel_hi:[1,0]
	v_pk_mul_f32 v[42:43], v[42:43], v[96:97] op_sel_hi:[1,0]
	v_pk_mul_f32 v[40:41], v[40:41], v[96:97] op_sel_hi:[1,0]
	v_pk_mul_f32 v[38:39], v[38:39], v[96:97] op_sel_hi:[1,0]
	v_pk_mul_f32 v[36:37], v[36:37], v[96:97] op_sel_hi:[1,0]
	v_pk_mul_f32 v[34:35], v[34:35], v[96:97] op_sel_hi:[1,0]
	v_pk_mul_f32 v[32:33], v[32:33], v[96:97] op_sel_hi:[1,0]
	v_pk_mul_f32 v[62:63], v[62:63], v[96:97] op_sel_hi:[1,0]
	v_pk_mul_f32 v[60:61], v[60:61], v[96:97] op_sel_hi:[1,0]
	v_pk_mul_f32 v[58:59], v[58:59], v[96:97] op_sel_hi:[1,0]
	v_pk_mul_f32 v[56:57], v[56:57], v[96:97] op_sel_hi:[1,0]
	v_pk_mul_f32 v[54:55], v[54:55], v[96:97] op_sel_hi:[1,0]
	v_pk_mul_f32 v[52:53], v[52:53], v[96:97] op_sel_hi:[1,0]
	v_pk_mul_f32 v[50:51], v[50:51], v[96:97] op_sel_hi:[1,0]
	v_pk_mul_f32 v[48:49], v[48:49], v[96:97] op_sel_hi:[1,0]
.LBB0_417:
	v_sub_f32_e32 v64, v160, v98
	v_exp_f32_e32 v160, v64
	v_sub_f32_e32 v64, v161, v98
	v_exp_f32_e32 v161, v64
	v_sub_f32_e32 v64, v162, v98
	v_exp_f32_e32 v162, v64
	v_sub_f32_e32 v64, v163, v98
	v_exp_f32_e32 v163, v64
	v_sub_f32_e32 v65, v164, v98
	v_add_f32_e32 v64, 0, v160
	v_exp_f32_e32 v164, v65
	v_sub_f32_e32 v65, v165, v98
	v_add_f32_e32 v64, v161, v64
	v_exp_f32_e32 v165, v65
	v_sub_f32_e32 v65, v166, v98
	v_add_f32_e32 v64, v162, v64
	v_exp_f32_e32 v166, v65
	v_sub_f32_e32 v65, v167, v98
	v_add_f32_e32 v64, v163, v64
	v_exp_f32_e32 v167, v65
	v_add_f32_e32 v64, v164, v64
	v_add_f32_e32 v64, v165, v64
	v_add_f32_e32 v64, v166, v64
	v_add_f32_e32 v88, v167, v64
	v_sub_f32_e32 v64, v168, v98
	v_exp_f32_e32 v168, v64
	v_sub_f32_e32 v64, v169, v98
	v_exp_f32_e32 v169, v64
	v_sub_f32_e32 v64, v170, v98
	v_exp_f32_e32 v170, v64
	v_sub_f32_e32 v64, v171, v98
	v_exp_f32_e32 v171, v64
	v_sub_f32_e32 v64, v172, v98
	v_exp_f32_e32 v172, v64
	v_sub_f32_e32 v64, v173, v98
	v_exp_f32_e32 v173, v64
	v_sub_f32_e32 v64, v174, v98
	v_exp_f32_e32 v174, v64
	v_sub_f32_e32 v64, v175, v98
	v_exp_f32_e32 v175, v64
	v_sub_f32_e32 v64, v176, v98
	v_exp_f32_e32 v176, v64
	v_sub_f32_e32 v64, v177, v98
	v_exp_f32_e32 v177, v64
	v_sub_f32_e32 v64, v178, v98
	v_exp_f32_e32 v178, v64
	v_sub_f32_e32 v64, v179, v98
	v_exp_f32_e32 v179, v64
	v_sub_f32_e32 v64, v180, v98
	v_exp_f32_e32 v180, v64
	v_sub_f32_e32 v64, v181, v98
	v_exp_f32_e32 v181, v64
	v_sub_f32_e32 v64, v182, v98
	v_exp_f32_e32 v182, v64
	v_sub_f32_e32 v64, v183, v98
	v_exp_f32_e32 v183, v64
	v_sub_f32_e32 v64, v184, v98
	v_exp_f32_e32 v184, v64
	v_sub_f32_e32 v64, v185, v98
	v_exp_f32_e32 v185, v64
	v_sub_f32_e32 v64, v186, v98
	v_add_u32_e32 v89, v247, v243
	v_exp_f32_e32 v186, v64
	ds_read_b128 v[64:67], v89 offset:36864
	ds_read_b128 v[72:75], v89 offset:36896
	v_sub_f32_e32 v68, v187, v98
	v_exp_f32_e32 v187, v68
	v_sub_f32_e32 v68, v188, v98
	v_exp_f32_e32 v188, v68
	v_cvt_pk_bf16_f32 v68, v160, v161
	v_cvt_pk_bf16_f32 v69, v162, v163
	v_cvt_pk_bf16_f32 v70, v164, v165
	v_cvt_pk_bf16_f32 v71, v166, v167
	ds_read_b128 v[76:79], v89 offset:36928
	ds_read_b128 v[80:83], v89 offset:36960
	s_waitcnt lgkmcnt(3)
	v_mfma_f32_32x32x16_bf16 v[32:47], v[64:67], v[68:71], v[32:47]
	v_sub_f32_e32 v64, v189, v98
	v_exp_f32_e32 v189, v64
	v_cvt_pk_bf16_f32 v64, v168, v169
	v_cvt_pk_bf16_f32 v65, v170, v171
	v_cvt_pk_bf16_f32 v66, v172, v173
	v_cvt_pk_bf16_f32 v67, v174, v175
	ds_read_b128 v[84:87], v89 offset:41472
	s_waitcnt lgkmcnt(3)
	v_mfma_f32_32x32x16_bf16 v[32:47], v[72:75], v[64:67], v[32:47]
	v_sub_f32_e32 v72, v190, v98
	v_exp_f32_e32 v190, v72
	v_cvt_pk_bf16_f32 v72, v176, v177
	v_cvt_pk_bf16_f32 v73, v178, v179
	v_cvt_pk_bf16_f32 v74, v180, v181
	v_cvt_pk_bf16_f32 v75, v182, v183
	s_waitcnt lgkmcnt(2)
	s_nop 0
	v_mfma_f32_32x32x16_bf16 v[32:47], v[76:79], v[72:75], v[32:47]
	v_sub_f32_e32 v76, v191, v98
	v_exp_f32_e32 v191, v76
	v_cvt_pk_bf16_f32 v76, v184, v185
	v_cvt_pk_bf16_f32 v77, v186, v187
	v_cvt_pk_bf16_f32 v78, v188, v189
	v_cvt_pk_bf16_f32 v79, v190, v191
	s_waitcnt lgkmcnt(1)
	s_nop 0
	v_mfma_f32_32x32x16_bf16 v[32:47], v[80:83], v[76:79], v[32:47]
	v_add_f32_e32 v80, v168, v88
	v_add_f32_e32 v80, v169, v80
	v_add_f32_e32 v80, v170, v80
	v_add_f32_e32 v80, v171, v80
	v_add_f32_e32 v80, v172, v80
	v_add_f32_e32 v88, v173, v80
	ds_read_b128 v[80:83], v89 offset:41504
	s_waitcnt lgkmcnt(1)
	v_mfma_f32_32x32x16_bf16 v[48:63], v[84:87], v[68:71], v[48:63]
	v_add_f32_e32 v68, v174, v88
	v_add_f32_e32 v68, v175, v68
	v_add_f32_e32 v68, v176, v68
	v_add_f32_e32 v68, v177, v68
	v_add_f32_e32 v68, v178, v68
	v_add_f32_e32 v84, v179, v68
	ds_read_b128 v[68:71], v89 offset:41536
	s_waitcnt lgkmcnt(1)
	v_mfma_f32_32x32x16_bf16 v[48:63], v[80:83], v[64:67], v[48:63]
	v_add_f32_e32 v64, v180, v84
	v_add_f32_e32 v64, v181, v64
	v_add_f32_e32 v64, v182, v64
	v_add_f32_e32 v64, v183, v64
	v_add_f32_e32 v64, v184, v64
	v_add_f32_e32 v80, v185, v64
	ds_read_b128 v[64:67], v89 offset:41568
	s_waitcnt lgkmcnt(1)
	v_mfma_f32_32x32x16_bf16 v[48:63], v[68:71], v[72:75], v[48:63]
	v_add_f32_e32 v68, v186, v80
	v_add_f32_e32 v68, v187, v68
	v_add_f32_e32 v68, v188, v68
	v_add_f32_e32 v68, v189, v68
	v_add_f32_e32 v68, v190, v68
	v_add_f32_e32 v68, v191, v68
	v_fmac_f32_e32 v68, v250, v96
	s_waitcnt lgkmcnt(0)
	v_mfma_f32_32x32x16_bf16 v[48:63], v[64:67], v[76:79], v[48:63]
	v_mov_b32_e32 v250, v68
	s_nop 10
	v_mov_b64_e32 v[94:95], v[62:63]
	v_mov_b64_e32 v[92:93], v[60:61]
	v_mov_b64_e32 v[90:91], v[58:59]
	v_mov_b64_e32 v[88:89], v[56:57]
	v_mov_b64_e32 v[86:87], v[54:55]
	v_mov_b64_e32 v[84:85], v[52:53]
	v_mov_b64_e32 v[82:83], v[50:51]
	v_mov_b64_e32 v[80:81], v[48:49]
	s_and_b64 vcc, exec, s[40:41]
	s_cbranch_vccz .LBB0_419
	s_branch .LBB0_420

.LBB0_434:
	v_max_f32_e32 v48, v1, v1
	v_max_f32_e32 v49, v0, v0
	v_max_f32_e32 v48, v49, v48
	v_max3_f32 v48, v48, v2, v3
	v_max3_f32 v48, v48, v4, v5
	v_max3_f32 v48, v48, v6, v7
	v_max3_f32 v48, v48, v8, v9
	v_max3_f32 v48, v48, v10, v11
	v_max3_f32 v48, v48, v12, v13
	v_max3_f32 v48, v48, v14, v15
	v_max3_f32 v48, v48, v16, v17
	v_max3_f32 v48, v48, v18, v19
	v_max3_f32 v48, v48, v20, v21
	v_max3_f32 v48, v48, v22, v23
	v_max3_f32 v48, v48, v24, v25
	v_max3_f32 v48, v48, v26, v27
	v_max3_f32 v48, v48, v28, v29
	v_max3_f32 v48, v48, v30, v31
	v_mov_b32_e32 v49, v48
	v_mov_b32_e32 v50, v48
	s_nop 1
	v_permlane32_swap_b32_e32 v49, v50
	v_cndmask_b32_e64 v49, v49, v50, s[38:39]
	v_max3_f32 v131, v97, v48, v49
	v_cmp_neq_f32_e32 vcc, s2, v131
	s_nop 1
	v_cndmask_b32_e32 v49, 0, v131, vcc
	v_sub_f32_e32 v48, v97, v49
	v_exp_f32_e32 v48, v48
	s_nop 0
	v_cmp_eq_f32_e32 vcc, 1.0, v48
	s_cmp_eq_u64 vcc, exec
	s_cbranch_scc1 .LBB0_436
	v_pk_mul_f32 v[46:47], v[46:47], v[48:49] op_sel_hi:[1,0]
	v_pk_mul_f32 v[44:45], v[44:45], v[48:49] op_sel_hi:[1,0]
	v_pk_mul_f32 v[42:43], v[42:43], v[48:49] op_sel_hi:[1,0]
	v_pk_mul_f32 v[40:41], v[40:41], v[48:49] op_sel_hi:[1,0]
	v_pk_mul_f32 v[38:39], v[38:39], v[48:49] op_sel_hi:[1,0]
	v_pk_mul_f32 v[36:37], v[36:37], v[48:49] op_sel_hi:[1,0]
	v_pk_mul_f32 v[34:35], v[34:35], v[48:49] op_sel_hi:[1,0]
	v_pk_mul_f32 v[32:33], v[32:33], v[48:49] op_sel_hi:[1,0]
	v_pk_mul_f32 v[94:95], v[94:95], v[48:49] op_sel_hi:[1,0]
	v_pk_mul_f32 v[92:93], v[92:93], v[48:49] op_sel_hi:[1,0]
	v_pk_mul_f32 v[90:91], v[90:91], v[48:49] op_sel_hi:[1,0]
	v_pk_mul_f32 v[88:89], v[88:89], v[48:49] op_sel_hi:[1,0]
	v_pk_mul_f32 v[86:87], v[86:87], v[48:49] op_sel_hi:[1,0]
	v_pk_mul_f32 v[84:85], v[84:85], v[48:49] op_sel_hi:[1,0]
	v_pk_mul_f32 v[82:83], v[82:83], v[48:49] op_sel_hi:[1,0]
	v_pk_mul_f32 v[80:81], v[80:81], v[48:49] op_sel_hi:[1,0]
.LBB0_436:
	v_sub_f32_e32 v0, v0, v49
	v_exp_f32_e32 v0, v0
	v_sub_f32_e32 v1, v1, v49
	v_exp_f32_e32 v1, v1
	v_sub_f32_e32 v2, v2, v49
	v_exp_f32_e32 v2, v2
	v_sub_f32_e32 v3, v3, v49
	v_exp_f32_e32 v3, v3
	v_sub_f32_e32 v4, v4, v49
	v_add_f32_e32 v50, 0, v0
	v_exp_f32_e32 v4, v4
	v_sub_f32_e32 v5, v5, v49
	v_add_f32_e32 v50, v1, v50
	v_exp_f32_e32 v5, v5
	v_sub_f32_e32 v6, v6, v49
	v_add_f32_e32 v50, v2, v50
	v_exp_f32_e32 v6, v6
	v_sub_f32_e32 v7, v7, v49
	v_add_f32_e32 v50, v3, v50
	v_exp_f32_e32 v7, v7
	v_add_f32_e32 v50, v4, v50
	v_add_f32_e32 v50, v5, v50
	v_add_f32_e32 v50, v6, v50
	v_add_u32_e32 v75, v247, v243
	v_add_f32_e32 v74, v7, v50
	ds_read_b128 v[50:53], v75 offset:18432
	ds_read_b128 v[58:61], v75 offset:18464
	v_cvt_pk_bf16_f32 v54, v0, v1
	v_cvt_pk_bf16_f32 v55, v2, v3
	v_cvt_pk_bf16_f32 v56, v4, v5
	v_cvt_pk_bf16_f32 v57, v6, v7
	v_sub_f32_e32 v8, v8, v49
	v_sub_f32_e32 v9, v9, v49
	s_waitcnt lgkmcnt(1)
	v_mfma_f32_32x32x16_bf16 v[32:47], v[50:53], v[54:57], v[32:47]
	v_sub_f32_e32 v10, v10, v49
	v_sub_f32_e32 v11, v11, v49
	v_sub_f32_e32 v12, v12, v49
	v_sub_f32_e32 v13, v13, v49
	v_sub_f32_e32 v14, v14, v49
	v_sub_f32_e32 v15, v15, v49
	v_exp_f32_e32 v8, v8
	v_exp_f32_e32 v9, v9
	v_exp_f32_e32 v10, v10
	v_exp_f32_e32 v11, v11
	v_exp_f32_e32 v12, v12
	v_exp_f32_e32 v13, v13
	v_exp_f32_e32 v14, v14
	v_exp_f32_e32 v15, v15
	v_cvt_pk_bf16_f32 v50, v8, v9
	v_cvt_pk_bf16_f32 v51, v10, v11
	v_cvt_pk_bf16_f32 v52, v12, v13
	v_cvt_pk_bf16_f32 v53, v14, v15
	ds_read_b128 v[62:65], v75 offset:18496
	ds_read_b128 v[66:69], v75 offset:18528
	s_waitcnt lgkmcnt(2)
	v_mfma_f32_32x32x16_bf16 v[32:47], v[58:61], v[50:53], v[32:47]
	v_sub_f32_e32 v16, v16, v49
	v_sub_f32_e32 v17, v17, v49
	v_sub_f32_e32 v18, v18, v49
	v_sub_f32_e32 v19, v19, v49
	v_sub_f32_e32 v20, v20, v49
	v_sub_f32_e32 v21, v21, v49
	v_sub_f32_e32 v22, v22, v49
	v_sub_f32_e32 v23, v23, v49
	v_exp_f32_e32 v16, v16
	v_exp_f32_e32 v17, v17
	v_exp_f32_e32 v18, v18
	v_exp_f32_e32 v19, v19
	v_exp_f32_e32 v20, v20
	v_exp_f32_e32 v21, v21
	v_exp_f32_e32 v22, v22
	v_exp_f32_e32 v23, v23
	v_cvt_pk_bf16_f32 v58, v16, v17
	v_cvt_pk_bf16_f32 v59, v18, v19
	v_cvt_pk_bf16_f32 v60, v20, v21
	v_cvt_pk_bf16_f32 v61, v22, v23
	ds_read_b128 v[70:73], v75 offset:23040
	v_sub_f32_e32 v24, v24, v49
	s_waitcnt lgkmcnt(2)
	v_mfma_f32_32x32x16_bf16 v[32:47], v[62:65], v[58:61], v[32:47]
	v_sub_f32_e32 v25, v25, v49
	v_sub_f32_e32 v26, v26, v49
	v_sub_f32_e32 v27, v27, v49
	v_sub_f32_e32 v28, v28, v49
	v_sub_f32_e32 v29, v29, v49
	v_sub_f32_e32 v30, v30, v49
	v_sub_f32_e32 v31, v31, v49
	v_exp_f32_e32 v24, v24
	v_exp_f32_e32 v25, v25
	v_exp_f32_e32 v26, v26
	v_exp_f32_e32 v27, v27
	v_exp_f32_e32 v28, v28
	v_exp_f32_e32 v29, v29
	v_exp_f32_e32 v30, v30
	v_exp_f32_e32 v31, v31
	v_cvt_pk_bf16_f32 v62, v24, v25
	v_cvt_pk_bf16_f32 v63, v26, v27
	v_cvt_pk_bf16_f32 v64, v28, v29
	v_cvt_pk_bf16_f32 v65, v30, v31
	v_add_f32_e32 v49, v8, v74
	v_add_f32_e32 v49, v9, v49
	s_waitcnt lgkmcnt(1)
	v_mfma_f32_32x32x16_bf16 v[32:47], v[66:69], v[62:65], v[32:47]
	ds_read_b128 v[66:69], v75 offset:23072
	v_add_f32_e32 v49, v10, v49
	v_add_f32_e32 v49, v11, v49
	v_add_f32_e32 v49, v12, v49
	v_add_f32_e32 v49, v13, v49
	v_add_f32_e32 v49, v14, v49
	v_add_f32_e32 v49, v15, v49
	s_waitcnt lgkmcnt(1)
	v_mfma_f32_32x32x16_bf16 v[80:95], v[70:73], v[54:57], v[80:95]
	ds_read_b128 v[54:57], v75 offset:23104
	v_add_f32_e32 v49, v16, v49
	v_add_f32_e32 v49, v17, v49
	v_add_f32_e32 v49, v18, v49
	v_add_f32_e32 v49, v19, v49
	v_add_f32_e32 v49, v20, v49
	v_add_f32_e32 v49, v21, v49
	s_waitcnt lgkmcnt(1)
	v_mfma_f32_32x32x16_bf16 v[80:95], v[66:69], v[50:53], v[80:95]
	ds_read_b128 v[50:53], v75 offset:23136
	v_add_f32_e32 v49, v22, v49
	v_add_f32_e32 v49, v23, v49
	v_add_f32_e32 v49, v24, v49
	v_add_f32_e32 v49, v25, v49
	v_add_f32_e32 v49, v26, v49
	v_add_f32_e32 v49, v27, v49
	s_waitcnt lgkmcnt(1)
	v_mfma_f32_32x32x16_bf16 v[80:95], v[54:57], v[58:61], v[80:95]
	v_add_f32_e32 v49, v28, v49
	v_add_f32_e32 v49, v29, v49
	v_add_f32_e32 v49, v30, v49
	v_add_f32_e32 v66, v31, v49
	v_fmac_f32_e32 v66, v250, v48
	v_mov_b32_e32 v250, v66
	s_waitcnt lgkmcnt(0)
	v_mfma_f32_32x32x16_bf16 v[80:95], v[50:53], v[62:65], v[80:95]
	s_nop 11
	v_mov_b32_e32 v62, v94
	v_mov_b32_e32 v63, v95
	v_mov_b32_e32 v48, v80
	v_mov_b32_e32 v49, v81
	v_mov_b32_e32 v50, v82
	v_mov_b32_e32 v51, v83
	v_mov_b32_e32 v52, v84
	v_mov_b32_e32 v53, v85
	v_mov_b32_e32 v54, v86
	v_mov_b32_e32 v55, v87
	v_mov_b32_e32 v56, v88
	v_mov_b32_e32 v57, v89
	v_mov_b32_e32 v58, v90
	v_mov_b32_e32 v59, v91
	v_mov_b32_e32 v60, v92
	v_mov_b32_e32 v61, v93
	s_and_b64 vcc, exec, s[42:43]
	s_cbranch_vccz .LBB0_438
	s_branch .LBB0_439

.LBB0_453:
	v_max_f32_e32 v96, v161, v161
	v_max_f32_e32 v97, v160, v160
	v_max_f32_e32 v96, v97, v96
	v_max3_f32 v96, v96, v162, v163
	v_max3_f32 v96, v96, v164, v165
	v_max3_f32 v96, v96, v166, v167
	v_max3_f32 v96, v96, v168, v169
	v_max3_f32 v96, v96, v170, v171
	v_max3_f32 v96, v96, v172, v173
	v_max3_f32 v96, v96, v174, v175
	v_max3_f32 v96, v96, v176, v177
	v_max3_f32 v96, v96, v178, v179
	v_max3_f32 v96, v96, v180, v181
	v_max3_f32 v96, v96, v182, v183
	v_max3_f32 v96, v96, v184, v185
	v_max3_f32 v96, v96, v186, v187
	v_max3_f32 v96, v96, v188, v189
	v_max3_f32 v96, v96, v190, v191
	v_mov_b32_e32 v97, v96
	v_mov_b32_e32 v98, v96
	s_nop 1
	v_permlane32_swap_b32_e32 v97, v98
	v_cndmask_b32_e64 v97, v97, v98, s[38:39]
	v_max3_f32 v97, v131, v96, v97
	v_cmp_neq_f32_e32 vcc, s2, v97
	s_nop 1
	v_cndmask_b32_e32 v98, 0, v97, vcc
	v_sub_f32_e32 v96, v131, v98
	v_exp_f32_e32 v96, v96
	s_nop 0
	v_cmp_eq_f32_e32 vcc, 1.0, v96
	s_cmp_eq_u64 vcc, exec
	s_cbranch_scc1 .LBB0_455
	v_pk_mul_f32 v[46:47], v[46:47], v[96:97] op_sel_hi:[1,0]
	v_pk_mul_f32 v[44:45], v[44:45], v[96:97] op_sel_hi:[1,0]
	v_pk_mul_f32 v[42:43], v[42:43], v[96:97] op_sel_hi:[1,0]
	v_pk_mul_f32 v[40:41], v[40:41], v[96:97] op_sel_hi:[1,0]
	v_pk_mul_f32 v[38:39], v[38:39], v[96:97] op_sel_hi:[1,0]
	v_pk_mul_f32 v[36:37], v[36:37], v[96:97] op_sel_hi:[1,0]
	v_pk_mul_f32 v[34:35], v[34:35], v[96:97] op_sel_hi:[1,0]
	v_pk_mul_f32 v[32:33], v[32:33], v[96:97] op_sel_hi:[1,0]
	v_pk_mul_f32 v[62:63], v[62:63], v[96:97] op_sel_hi:[1,0]
	v_pk_mul_f32 v[60:61], v[60:61], v[96:97] op_sel_hi:[1,0]
	v_pk_mul_f32 v[58:59], v[58:59], v[96:97] op_sel_hi:[1,0]
	v_pk_mul_f32 v[56:57], v[56:57], v[96:97] op_sel_hi:[1,0]
	v_pk_mul_f32 v[54:55], v[54:55], v[96:97] op_sel_hi:[1,0]
	v_pk_mul_f32 v[52:53], v[52:53], v[96:97] op_sel_hi:[1,0]
	v_pk_mul_f32 v[50:51], v[50:51], v[96:97] op_sel_hi:[1,0]
	v_pk_mul_f32 v[48:49], v[48:49], v[96:97] op_sel_hi:[1,0]
.LBB0_455:
	v_sub_f32_e32 v64, v160, v98
	v_exp_f32_e32 v160, v64
	v_sub_f32_e32 v64, v161, v98
	v_exp_f32_e32 v161, v64
	v_sub_f32_e32 v64, v162, v98
	v_exp_f32_e32 v162, v64
	v_sub_f32_e32 v64, v163, v98
	v_exp_f32_e32 v163, v64
	v_sub_f32_e32 v65, v164, v98
	v_add_f32_e32 v64, 0, v160
	v_exp_f32_e32 v164, v65
	v_sub_f32_e32 v65, v165, v98
	v_add_f32_e32 v64, v161, v64
	v_exp_f32_e32 v165, v65
	v_sub_f32_e32 v65, v166, v98
	v_add_f32_e32 v64, v162, v64
	v_exp_f32_e32 v166, v65
	v_sub_f32_e32 v65, v167, v98
	v_add_f32_e32 v64, v163, v64
	v_exp_f32_e32 v167, v65
	v_add_f32_e32 v64, v164, v64
	v_add_f32_e32 v64, v165, v64
	v_add_f32_e32 v64, v166, v64
	v_add_f32_e32 v88, v167, v64
	v_sub_f32_e32 v64, v168, v98
	v_exp_f32_e32 v168, v64
	v_sub_f32_e32 v64, v169, v98
	v_exp_f32_e32 v169, v64
	v_sub_f32_e32 v64, v170, v98
	v_exp_f32_e32 v170, v64
	v_sub_f32_e32 v64, v171, v98
	v_exp_f32_e32 v171, v64
	v_sub_f32_e32 v64, v172, v98
	v_exp_f32_e32 v172, v64
	v_sub_f32_e32 v64, v173, v98
	v_exp_f32_e32 v173, v64
	v_sub_f32_e32 v64, v174, v98
	v_exp_f32_e32 v174, v64
	v_sub_f32_e32 v64, v175, v98
	v_exp_f32_e32 v175, v64
	v_sub_f32_e32 v64, v176, v98
	v_exp_f32_e32 v176, v64
	v_sub_f32_e32 v64, v177, v98
	v_exp_f32_e32 v177, v64
	v_sub_f32_e32 v64, v178, v98
	v_exp_f32_e32 v178, v64
	v_sub_f32_e32 v64, v179, v98
	v_exp_f32_e32 v179, v64
	v_sub_f32_e32 v64, v180, v98
	v_exp_f32_e32 v180, v64
	v_sub_f32_e32 v64, v181, v98
	v_exp_f32_e32 v181, v64
	v_sub_f32_e32 v64, v182, v98
	v_exp_f32_e32 v182, v64
	v_sub_f32_e32 v64, v183, v98
	v_exp_f32_e32 v183, v64
	v_sub_f32_e32 v64, v184, v98
	v_exp_f32_e32 v184, v64
	v_sub_f32_e32 v64, v185, v98
	v_exp_f32_e32 v185, v64
	v_sub_f32_e32 v64, v186, v98
	v_add_u32_e32 v89, v247, v243
	v_exp_f32_e32 v186, v64
	ds_read_b128 v[64:67], v89 offset:36864
	ds_read_b128 v[72:75], v89 offset:36896
	v_sub_f32_e32 v68, v187, v98
	v_exp_f32_e32 v187, v68
	v_sub_f32_e32 v68, v188, v98
	v_exp_f32_e32 v188, v68
	v_cvt_pk_bf16_f32 v68, v160, v161
	v_cvt_pk_bf16_f32 v69, v162, v163
	v_cvt_pk_bf16_f32 v70, v164, v165
	v_cvt_pk_bf16_f32 v71, v166, v167
	ds_read_b128 v[76:79], v89 offset:36928
	ds_read_b128 v[80:83], v89 offset:36960
	s_waitcnt lgkmcnt(3)
	v_mfma_f32_32x32x16_bf16 v[32:47], v[64:67], v[68:71], v[32:47]
	v_sub_f32_e32 v64, v189, v98
	v_exp_f32_e32 v189, v64
	v_cvt_pk_bf16_f32 v64, v168, v169
	v_cvt_pk_bf16_f32 v65, v170, v171
	v_cvt_pk_bf16_f32 v66, v172, v173
	v_cvt_pk_bf16_f32 v67, v174, v175
	ds_read_b128 v[84:87], v89 offset:41472
	s_waitcnt lgkmcnt(3)
	v_mfma_f32_32x32x16_bf16 v[32:47], v[72:75], v[64:67], v[32:47]
	v_sub_f32_e32 v72, v190, v98
	v_exp_f32_e32 v190, v72
	v_cvt_pk_bf16_f32 v72, v176, v177
	v_cvt_pk_bf16_f32 v73, v178, v179
	v_cvt_pk_bf16_f32 v74, v180, v181
	v_cvt_pk_bf16_f32 v75, v182, v183
	s_waitcnt lgkmcnt(2)
	s_nop 0
	v_mfma_f32_32x32x16_bf16 v[32:47], v[76:79], v[72:75], v[32:47]
	v_sub_f32_e32 v76, v191, v98
	v_exp_f32_e32 v191, v76
	v_cvt_pk_bf16_f32 v76, v184, v185
	v_cvt_pk_bf16_f32 v77, v186, v187
	v_cvt_pk_bf16_f32 v78, v188, v189
	v_cvt_pk_bf16_f32 v79, v190, v191
	s_waitcnt lgkmcnt(1)
	s_nop 0
	v_mfma_f32_32x32x16_bf16 v[32:47], v[80:83], v[76:79], v[32:47]
	v_add_f32_e32 v80, v168, v88
	v_add_f32_e32 v80, v169, v80
	v_add_f32_e32 v80, v170, v80
	v_add_f32_e32 v80, v171, v80
	v_add_f32_e32 v80, v172, v80
	v_add_f32_e32 v88, v173, v80
	ds_read_b128 v[80:83], v89 offset:41504
	s_waitcnt lgkmcnt(1)
	v_mfma_f32_32x32x16_bf16 v[48:63], v[84:87], v[68:71], v[48:63]
	v_add_f32_e32 v68, v174, v88
	v_add_f32_e32 v68, v175, v68
	v_add_f32_e32 v68, v176, v68
	v_add_f32_e32 v68, v177, v68
	v_add_f32_e32 v68, v178, v68
	v_add_f32_e32 v84, v179, v68
	ds_read_b128 v[68:71], v89 offset:41536
	s_waitcnt lgkmcnt(1)
	v_mfma_f32_32x32x16_bf16 v[48:63], v[80:83], v[64:67], v[48:63]
	v_add_f32_e32 v64, v180, v84
	v_add_f32_e32 v64, v181, v64
	v_add_f32_e32 v64, v182, v64
	v_add_f32_e32 v64, v183, v64
	v_add_f32_e32 v64, v184, v64
	v_add_f32_e32 v80, v185, v64
	ds_read_b128 v[64:67], v89 offset:41568
	s_waitcnt lgkmcnt(1)
	v_mfma_f32_32x32x16_bf16 v[48:63], v[68:71], v[72:75], v[48:63]
	v_add_f32_e32 v68, v186, v80
	v_add_f32_e32 v68, v187, v68
	v_add_f32_e32 v68, v188, v68
	v_add_f32_e32 v68, v189, v68
	v_add_f32_e32 v68, v190, v68
	v_add_f32_e32 v68, v191, v68
	v_fmac_f32_e32 v68, v250, v96
	s_waitcnt lgkmcnt(0)
	v_mfma_f32_32x32x16_bf16 v[48:63], v[64:67], v[76:79], v[48:63]
	v_mov_b32_e32 v250, v68
	s_nop 10
	s_and_b64 vcc, exec, s[40:41]
	s_cbranch_vccz .LBB0_457
	s_branch .LBB0_458

.LBB0_460:
	v_mov_b32_e32 v0, v250
	v_mov_b32_e32 v1, v250
	s_nop 1
	v_permlane32_swap_b32_e32 v0, v1
	v_cndmask_b32_e64 v0, v0, v1, s[38:39]
	v_add_f32_e32 v0, v250, v0
	v_div_scale_f32 v1, s[4:5], v0, v0, 1.0
	v_rcp_f32_e32 v2, v1
	v_readlane_b32 s4, v255, 38
	s_add_i32 s4, s4, s30
	v_lshrrev_b32_e32 v66, 2, v246
	v_fma_f32 v3, -v1, v2, 1.0
	v_fmac_f32_e32 v2, v3, v2
	v_div_scale_f32 v3, vcc, 1.0, v0, 1.0
	v_and_or_b32 v64, v246, 31, s4
	v_mul_f32_e32 v4, v3, v2
	v_lshl_add_u32 v64, s26, 5, v64
	v_fma_f32 v5, -v1, v4, v3
	v_ashrrev_i32_e32 v65, 31, v64
	v_readlane_b32 s4, v255, 13
	v_fmac_f32_e32 v4, v5, v2
	v_lshlrev_b64 v[64:65], 12, v[64:65]
	v_readlane_b32 s5, v255, 14
	v_fma_f32 v1, -v1, v4, v3
	v_div_fmas_f32 v1, v1, v2, v4
	v_lshl_add_u64 v[64:65], s[4:5], 0, v[64:65]
	v_readlane_b32 s4, v254, 19
	v_readlane_b32 s5, v254, 20
	v_readlane_b32 s4, v255, 39
	v_div_fixup_f32 v0, v1, v0, 1.0
	s_mov_b32 s7, s5
	s_lshl_b32 s6, s4, 1
	v_pk_mul_f32 v[2:3], v[46:47], v[0:1] op_sel_hi:[1,0]
	v_pk_mul_f32 v[4:5], v[44:45], v[0:1] op_sel_hi:[1,0]
	v_pk_mul_f32 v[6:7], v[42:43], v[0:1] op_sel_hi:[1,0]
	v_pk_mul_f32 v[8:9], v[40:41], v[0:1] op_sel_hi:[1,0]
	v_pk_mul_f32 v[10:11], v[38:39], v[0:1] op_sel_hi:[1,0]
	v_pk_mul_f32 v[12:13], v[36:37], v[0:1] op_sel_hi:[1,0]
	v_pk_mul_f32 v[14:15], v[34:35], v[0:1] op_sel_hi:[1,0]
	v_pk_mul_f32 v[16:17], v[32:33], v[0:1] op_sel_hi:[1,0]
	v_pk_mul_f32 v[18:19], v[62:63], v[0:1] op_sel_hi:[1,0]
	v_pk_mul_f32 v[20:21], v[60:61], v[0:1] op_sel_hi:[1,0]
	v_pk_mul_f32 v[22:23], v[58:59], v[0:1] op_sel_hi:[1,0]
	v_pk_mul_f32 v[24:25], v[56:57], v[0:1] op_sel_hi:[1,0]
	v_pk_mul_f32 v[26:27], v[54:55], v[0:1] op_sel_hi:[1,0]
	v_pk_mul_f32 v[28:29], v[52:53], v[0:1] op_sel_hi:[1,0]
	v_pk_mul_f32 v[30:31], v[50:51], v[0:1] op_sel_hi:[1,0]
	v_pk_mul_f32 v[0:1], v[48:49], v[0:1] op_sel_hi:[1,0]
	v_lshl_add_u64 v[64:65], v[64:65], 0, s[6:7]
	v_and_b32_e32 v128, 8, v66
	v_lshl_add_u64 v[64:65], v[64:65], 0, v[128:129]
	v_cvt_pk_bf16_f32 v0, v0, v1
	v_cvt_pk_bf16_f32 v1, v30, v31
	v_writelane_b32 v254, s4, 19
	global_store_dwordx2 v[64:65], v[0:1], off offset:64
	v_cvt_pk_bf16_f32 v0, v28, v29
	v_cvt_pk_bf16_f32 v1, v26, v27
	v_writelane_b32 v254, s5, 20
	v_cvt_pk_bf16_f32 v16, v16, v17
	v_cvt_pk_bf16_f32 v17, v14, v15
	v_cvt_pk_bf16_f32 v12, v12, v13
	v_cvt_pk_bf16_f32 v13, v10, v11
	v_cvt_pk_bf16_f32 v8, v8, v9
	v_cvt_pk_bf16_f32 v9, v6, v7
	v_cvt_pk_bf16_f32 v4, v4, v5
	v_cvt_pk_bf16_f32 v5, v2, v3
	global_store_dwordx2 v[64:65], v[0:1], off offset:80
	v_cvt_pk_bf16_f32 v0, v24, v25
	v_cvt_pk_bf16_f32 v1, v22, v23
	s_mov_b64 s[4:5], 0x70
	v_readlane_b32 s30, v255, 3
	v_readlane_b32 s22, v255, 16
	global_store_dwordx2 v[64:65], v[16:17], off
	global_store_dwordx2 v[64:65], v[12:13], off offset:16
	global_store_dwordx2 v[64:65], v[8:9], off offset:32
	global_store_dwordx2 v[64:65], v[4:5], off offset:48
	global_store_dwordx2 v[64:65], v[0:1], off offset:96
	v_cvt_pk_bf16_f32 v0, v20, v21
	v_cvt_pk_bf16_f32 v1, v18, v19
	v_lshl_add_u64 v[2:3], v[64:65], 0, s[4:5]
	s_mov_b64 s[4:5], 0
	v_readlane_b32 s31, v255, 4
	v_readlane_b32 s23, v255, 17
	s_mul_hi_i32 s9, s27, 0x1800000
	s_mul_i32 s10, s27, 0x1800000
	s_waitcnt vmcnt(7)
	v_mov_b32_e32 v232, 1
	v_mov_b32_e32 v233, 0x260
	v_mov_b64_e32 v[234:235], 0x100
	v_mov_b64_e32 v[236:237], 0xff
	v_mov_b32_e32 v238, 0x42800000
	v_mov_b32_e32 v239, 6
	v_mov_b32_e32 v240, 4
	v_mov_b32_e32 v241, v249
	v_mov_b32_e32 v242, 12
